# stack 1 plus grid barrier non-leader L1 invalidate issued before the release spin instead of after it
# speedup vs baseline: 1.0135x; 1.0135x over previous
; __device__ __forceinline__ unsigned xb_ld(unsigned* p)              { return __hip_atomic_load(p, __ATOMIC_RELAXED, __HIP_MEMORY_SCOPE_AGENT); }
; __device__ __forceinline__ unsigned xb_add(unsigned* p, unsigned v) { return __hip_atomic_fetch_add(p, v, __ATOMIC_RELAXED, __HIP_MEMORY_SCOPE_AGENT); }
; #define XB_SPIN(cond, bar) do { unsigned _sp = 0; while (cond) { __builtin_amdgcn_s_sleep(1); \
;     if ((++_sp & 255u) == 0u) { if (xb_ld(&(bar)[XB_TMO])) break; if (_sp > XB_SPIN_CAP) { atomicAdd(&(bar)[XB_TMO], 1u); break; } } } } while (0)
; __device__ __forceinline__ void xcd_barrier(const XcdBarrier& b, int tid_in) {
;     ...
;         const unsigned old = xb_add(&bar[XB_XSUB(b.x)], 1u);
;         const unsigned gen = old / nloc;
;         if (old + 1u == (gen + 1u) * nloc) {
;             __builtin_amdgcn_fence(__ATOMIC_RELEASE, "agent");
;             asm volatile("s_waitcnt vmcnt(0)" ::: "memory");
;             const unsigned og = xb_add(&bar[XB_TOP], 1u);
;             const unsigned tg = og / nx;
;             if (og + 1u == (tg + 1u) * nx) xb_add(&bar[XB_TOPGEN], 1u);
;             else XB_SPIN(xb_ld(&bar[XB_TOPGEN]) == tg, bar);
;             __builtin_amdgcn_fence(__ATOMIC_ACQUIRE, "agent");
;             xb_add(&bar[XB_XGEN(b.x)], 1u);
;             asm volatile("s_waitcnt vmcnt(0)" ::: "memory");
;         } else {
;             XB_SPIN(xb_ld(&bar[XB_XGEN(b.x)]) == gen, bar);
;             __builtin_amdgcn_fence(__ATOMIC_ACQUIRE, "agent");
;             asm volatile("s_waitcnt vmcnt(0)" ::: "memory");
.LBB0_531:
	v_readlane_b32 s4, v253, 41
	s_add_u32 s26, s0, s4
	s_addc_u32 s25, s1, 0
	v_mov_b32_e32 v1, s26
	v_add_co_u32_e32 v4, vcc, 0x1000, v1
	v_mov_b32_e32 v1, s25
	s_nop 0
	v_addc_co_u32_e32 v5, vcc, 0, v1, vcc
	flat_atomic_add v3, v[4:5], v221 offset:1024 sc0
	v_cvt_f32_u32_e32 v1, v2
	v_sub_u32_e32 v4, 0, v2
	v_rcp_iflag_f32_e32 v1, v1
	s_nop 0
	v_mul_f32_e32 v1, 0x4f7ffffe, v1
	v_cvt_u32_f32_e32 v1, v1
	v_mul_lo_u32 v4, v4, v1
	v_mul_hi_u32 v4, v1, v4
	v_add_u32_e32 v1, v1, v4
	s_waitcnt vmcnt(0) lgkmcnt(0)
	v_mul_hi_u32 v1, v3, v1
	v_mul_lo_u32 v4, v1, v2
	v_sub_u32_e32 v4, v3, v4
	v_cmp_ge_u32_e32 vcc, v4, v2
	v_add_u32_e32 v5, 1, v1
	s_nop 0
	v_cndmask_b32_e32 v1, v1, v5, vcc
	v_sub_u32_e32 v5, v4, v2
	v_cndmask_b32_e32 v4, v4, v5, vcc
	v_cmp_ge_u32_e32 vcc, v4, v2
	v_add_u32_e32 v4, 1, v1
	s_nop 0
	v_cndmask_b32_e32 v1, v1, v4, vcc
	v_add_u32_e32 v4, 1, v3
	v_mad_u64_u32 v[2:3], s[4:5], v2, v1, v[2:3]
	v_cmp_ne_u32_e32 vcc, v4, v2
	s_and_saveexec_b64 s[4:5], vcc
	s_xor_b64 s[4:5], exec, s[4:5]
	s_cbranch_execz .LBB0_552
	buffer_inv sc1
	v_mov_b32_e32 v0, s26
	v_add_co_u32_e32 v2, vcc, 0x2000, v0
	v_mov_b32_e32 v0, s25
	s_nop 0
	v_addc_co_u32_e32 v3, vcc, 0, v0, vcc
	flat_load_dword v0, v[2:3] offset:1024 sc1
	s_add_u32 s8, s26, 0x2400
	s_addc_u32 s9, s25, 0
	s_waitcnt vmcnt(0) lgkmcnt(0)
	v_cmp_eq_u32_e32 vcc, v0, v1
	s_and_saveexec_b64 s[6:7], vcc
	s_cbranch_execz .LBB0_551
	s_mov_b32 s27, 1
	s_mov_b64 s[10:11], 0
	s_branch .LBB0_535

; __device__ __forceinline__ unsigned xb_ld(unsigned* p)              { return __hip_atomic_load(p, __ATOMIC_RELAXED, __HIP_MEMORY_SCOPE_AGENT); }
; __device__ __forceinline__ unsigned xb_add(unsigned* p, unsigned v) { return __hip_atomic_fetch_add(p, v, __ATOMIC_RELAXED, __HIP_MEMORY_SCOPE_AGENT); }
; #define XB_SPIN(cond, bar) do { unsigned _sp = 0; while (cond) { __builtin_amdgcn_s_sleep(1); \
;     if ((++_sp & 255u) == 0u) { if (xb_ld(&(bar)[XB_TMO])) break; if (_sp > XB_SPIN_CAP) { atomicAdd(&(bar)[XB_TMO], 1u); break; } } } } while (0)
; __device__ __forceinline__ void xcd_barrier(const XcdBarrier& b, int tid_in) {
;     ...
;             __builtin_amdgcn_fence(__ATOMIC_RELEASE, "agent");
;             asm volatile("s_waitcnt vmcnt(0)" ::: "memory");
;             const unsigned og = xb_add(&bar[XB_TOP], 1u);
;             const unsigned tg = og / nx;
;             if (og + 1u == (tg + 1u) * nx) xb_add(&bar[XB_TOPGEN], 1u);
;             else XB_SPIN(xb_ld(&bar[XB_TOPGEN]) == tg, bar);
;     ...
;             XB_SPIN(xb_ld(&bar[XB_XGEN(b.x)]) == gen, bar);
;             __builtin_amdgcn_fence(__ATOMIC_ACQUIRE, "agent");
;             asm volatile("s_waitcnt vmcnt(0)" ::: "memory");
.LBB0_551:
	s_or_b64 exec, exec, s[6:7]
	s_waitcnt vmcnt(0) lgkmcnt(0)
.LBB0_552:
	s_andn2_saveexec_b64 s[4:5], s[4:5]
	s_cbranch_execz .LBB0_8
	v_mov_b32_e32 v1, s0
	v_add_co_u32_e32 v2, vcc, 0x3000, v1
	v_mov_b32_e32 v1, s1
	buffer_wbl2 sc1
	s_waitcnt vmcnt(0)
	v_addc_co_u32_e32 v3, vcc, 0, v1, vcc
	flat_atomic_add v1, v[2:3], v221 offset:1024 sc0
	v_cvt_f32_u32_e32 v2, v0
	v_sub_u32_e32 v3, 0, v0
	s_mov_b64 s[8:9], -1
	v_rcp_iflag_f32_e32 v2, v2
	s_nop 0
	v_mul_f32_e32 v2, 0x4f7ffffe, v2
	v_cvt_u32_f32_e32 v2, v2
	v_mul_lo_u32 v3, v3, v2
	v_mul_hi_u32 v3, v2, v3
	v_add_u32_e32 v2, v2, v3
	s_waitcnt vmcnt(0) lgkmcnt(0)
	v_mul_hi_u32 v2, v1, v2
	v_mul_lo_u32 v3, v2, v0
	v_sub_u32_e32 v3, v1, v3
	v_cmp_ge_u32_e32 vcc, v3, v0
	v_add_u32_e32 v4, 1, v2
	s_nop 0
	v_cndmask_b32_e32 v2, v2, v4, vcc
	v_sub_u32_e32 v4, v3, v0
	v_cndmask_b32_e32 v3, v3, v4, vcc
	v_cmp_ge_u32_e32 vcc, v3, v0
	v_add_u32_e32 v3, 1, v2
	s_nop 0
	v_cndmask_b32_e32 v2, v2, v3, vcc
	v_add_u32_e32 v3, 1, v1
	v_mad_u64_u32 v[0:1], s[4:5], v0, v2, v[0:1]
	s_add_u32 s4, s0, 0x3500
	s_addc_u32 s5, s1, 0
	v_cmp_ne_u32_e32 vcc, v3, v0
	v_mov_b64_e32 v[0:1], s[4:5]
	s_and_saveexec_b64 s[6:7], vcc
	s_cbranch_execz .LBB0_565
	v_mov_b64_e32 v[0:1], s[4:5]
	flat_load_dword v0, v[0:1] sc1
	s_mov_b64 s[12:13], 0
	s_waitcnt vmcnt(0) lgkmcnt(0)
	v_cmp_eq_u32_e32 vcc, v0, v2
	s_and_saveexec_b64 s[10:11], vcc
	s_cbranch_execz .LBB0_564
	s_add_u32 s8, s0, 0x200
	s_addc_u32 s9, s1, 0
	s_mov_b32 s22, 1
	s_mov_b64 s[0:1], 0
	s_branch .LBB0_557
